# dnprep x-init rewritten with batched LDS reads and readlane factors; permlane-swap max in all attention variants
# speedup vs baseline: 1.0430x; 1.0062x over previous
.LBB0_732:
	s_or_b64 exec, exec, s[2:3]
	v_and_b32_e32 v40, 15, v175
	v_lshlrev_b32_e32 v0, 4, v96
	v_or_b32_e32 v2, v0, v40
	v_and_b32_e32 v3, 48, v94
	v_mul_u32_u24_e32 v2, 0x48, v2
	v_add_u32_e32 v10, v174, v3
	s_movk_i32 s2, 0x90
	v_lshl_add_u32 v11, v2, 1, v10
	v_mad_u32_u24 v54, v40, s2, v10
	ds_read_b128 v[2:5], v11 offset:9216
	ds_read_b128 v[6:9], v11
	ds_read_b128 v[42:45], v11 offset:9280
	ds_read_b128 v[46:49], v11 offset:64
	ds_read_b128 v[10:13], v54 offset:9216
	ds_read_b128 v[18:21], v54 offset:9280
	s_waitcnt lgkmcnt(0)
	v_mfma_f32_16x16x32_bf16 v[14:17], v[2:5], v[10:13], 0
	v_or_b32_e32 v41, v41, v94
	ds_read_b128 v[50:53], v54 offset:13888
	v_mfma_f32_16x16x32_bf16 v[10:13], v[6:9], v[10:13], 0
	v_mfma_f32_16x16x32_bf16 v[26:29], v[46:49], v[18:21], v[10:13]
	v_mfma_f32_16x16x32_bf16 v[30:33], v[42:45], v[18:21], v[14:17]
	s_nop 5
	ds_read_b128 v[10:13], v54 offset:11520
	ds_read_b128 v[18:21], v54 offset:11584
	s_waitcnt lgkmcnt(0)
	v_mfma_f32_16x16x32_bf16 v[14:17], v[2:5], v[10:13], 0
	v_mfma_f32_16x16x32_bf16 v[10:13], v[6:9], v[10:13], 0
	v_mfma_f32_16x16x32_bf16 v[22:25], v[42:45], v[18:21], v[14:17]
	v_mfma_f32_16x16x32_bf16 v[18:21], v[46:49], v[18:21], v[10:13]
	s_nop 5
	ds_read_b128 v[10:13], v54 offset:13824
	s_waitcnt lgkmcnt(0)
	v_mfma_f32_16x16x32_bf16 v[14:17], v[2:5], v[10:13], 0
	v_mfma_f32_16x16x32_bf16 v[10:13], v[6:9], v[10:13], 0
	v_mfma_f32_16x16x32_bf16 v[14:17], v[42:45], v[50:53], v[14:17]
	v_mfma_f32_16x16x32_bf16 v[10:13], v[46:49], v[50:53], v[10:13]
	ds_read_b128 v[50:53], v54 offset:16128
	ds_read_b128 v[54:57], v54 offset:16192
	s_waitcnt lgkmcnt(0)
	v_mfma_f32_16x16x32_bf16 v[2:5], v[2:5], v[50:53], 0
	v_mfma_f32_16x16x32_bf16 v[50:53], v[6:9], v[50:53], 0
	v_mfma_f32_16x16x32_bf16 v[6:9], v[42:45], v[54:57], v[2:5]
	v_lshrrev_b32_e32 v42, 7, v142
	v_and_b32_e32 v43, 64, v175
	v_lshl_add_u32 v58, v42, 8, v95
	v_cmp_ne_u32_e32 vcc, 0, v43
	v_mfma_f32_16x16x32_bf16 v[2:5], v[46:49], v[54:57], v[50:53]
	v_lshl_add_u32 v212, v94, 2, v58
	ds_read_b32 v213, v212 offset:52736
	ds_read_b32 v214, v212 offset:52224
	v_lshl_add_u32 v215, v94, 2, v174
	v_mov_b32_e32 v216, 0x4000
	v_cndmask_b32_e64 v216, v216, 0, vcc
	v_add_u32_e32 v215, v215, v216
	v_mov_b32_e32 v217, 1.0
	s_waitcnt lgkmcnt(0)
	v_mul_f32_e32 v214, 0x3fb8aa3b, v214
	v_exp_f32_e32 v214, v214
	s_nop 0
	v_cndmask_b32_e32 v214, v217, v214, vcc
	v_mul_f32_e32 v213, v213, v214
	s_and_b64 s[2:3], s[0:1], exec
	s_cbranch_scc0 .Lxi_sd1
	ds_read_b32 v41, v215 offset:18432
	ds_read_b32 v43, v215 offset:18688
	ds_read_b32 v44, v215 offset:18944
	ds_read_b32 v45, v215 offset:19200
	ds_read_b32 v46, v215 offset:19456
	ds_read_b32 v47, v215 offset:19712
	ds_read_b32 v48, v215 offset:19968
	ds_read_b32 v49, v215 offset:20224
	ds_read_b32 v50, v215 offset:20480
	ds_read_b32 v51, v215 offset:20736
	ds_read_b32 v52, v215 offset:20992
	ds_read_b32 v53, v215 offset:21248
	ds_read_b32 v54, v215 offset:21504
	ds_read_b32 v55, v215 offset:21760
	ds_read_b32 v56, v215 offset:22016
	ds_read_b32 v57, v215 offset:22272
	s_waitcnt lgkmcnt(8)
	v_readlane_b32 s2, v213, 0
	v_readlane_b32 s3, v213, 1
	v_readlane_b32 s4, v213, 2
	v_readlane_b32 s5, v213, 3
	v_mul_f32_e32 v41, s2, v41
	v_mul_f32_e32 v43, s3, v43
	v_mul_f32_e32 v44, s4, v44
	v_mul_f32_e32 v45, s5, v45
	v_readlane_b32 s2, v213, 4
	v_readlane_b32 s3, v213, 5
	v_readlane_b32 s4, v213, 6
	v_readlane_b32 s5, v213, 7
	v_mul_f32_e32 v46, s2, v46
	v_mul_f32_e32 v47, s3, v47
	v_mul_f32_e32 v48, s4, v48
	v_mul_f32_e32 v49, s5, v49
	ds_read_b32 v59, v215 offset:22528
	ds_read_b32 v60, v215 offset:22784
	ds_read_b32 v61, v215 offset:23040
	ds_read_b32 v62, v215 offset:23296
	ds_read_b32 v63, v215 offset:23552
	ds_read_b32 v64, v215 offset:23808
	ds_read_b32 v65, v215 offset:24064
	ds_read_b32 v67, v215 offset:24320
	s_waitcnt lgkmcnt(8)
	v_readlane_b32 s2, v213, 8
	v_readlane_b32 s3, v213, 9
	v_readlane_b32 s4, v213, 10
	v_readlane_b32 s5, v213, 11
	v_mul_f32_e32 v50, s2, v50
	v_mul_f32_e32 v51, s3, v51
	v_mul_f32_e32 v52, s4, v52
	v_mul_f32_e32 v53, s5, v53
	v_readlane_b32 s2, v213, 12
	v_readlane_b32 s3, v213, 13
	v_readlane_b32 s4, v213, 14
	v_readlane_b32 s5, v213, 15
	v_mul_f32_e32 v54, s2, v54
	v_mul_f32_e32 v55, s3, v55
	v_mul_f32_e32 v56, s4, v56
	v_mul_f32_e32 v57, s5, v57
	ds_read_b32 v70, v215 offset:24576
	ds_read_b32 v71, v215 offset:24832
	ds_read_b32 v72, v215 offset:25088
	ds_read_b32 v74, v215 offset:25344
	ds_read_b32 v79, v215 offset:25600
	ds_read_b32 v78, v215 offset:25856
	ds_read_b32 v80, v215 offset:26112
	ds_read_b32 v82, v215 offset:26368
	s_waitcnt lgkmcnt(8)
	v_readlane_b32 s2, v213, 16
	v_readlane_b32 s3, v213, 17
	v_readlane_b32 s4, v213, 18
	v_readlane_b32 s5, v213, 19
	v_mul_f32_e32 v59, s2, v59
	v_mul_f32_e32 v60, s3, v60
	v_mul_f32_e32 v61, s4, v61
	v_mul_f32_e32 v62, s5, v62
	v_readlane_b32 s2, v213, 20
	v_readlane_b32 s3, v213, 21
	v_readlane_b32 s4, v213, 22
	v_readlane_b32 s5, v213, 23
	v_mul_f32_e32 v63, s2, v63
	v_mul_f32_e32 v64, s3, v64
	v_mul_f32_e32 v65, s4, v65
	v_mul_f32_e32 v67, s5, v67
	ds_read_b32 v89, v215 offset:26624
	ds_read_b32 v85, v215 offset:26880
	ds_read_b32 v87, v215 offset:27136
	ds_read_b32 v90, v215 offset:27392
	ds_read_b32 v105, v215 offset:27648
	ds_read_b32 v93, v215 offset:27904
	ds_read_b32 v96, v215 offset:28160
	ds_read_b32 v98, v215 offset:28416
	s_waitcnt lgkmcnt(8)
	v_readlane_b32 s2, v213, 24
	v_readlane_b32 s3, v213, 25
	v_readlane_b32 s4, v213, 26
	v_readlane_b32 s5, v213, 27
	v_mul_f32_e32 v70, s2, v70
	v_mul_f32_e32 v71, s3, v71
	v_mul_f32_e32 v72, s4, v72
	v_mul_f32_e32 v74, s5, v74
	v_readlane_b32 s2, v213, 28
	v_readlane_b32 s3, v213, 29
	v_readlane_b32 s4, v213, 30
	v_readlane_b32 s5, v213, 31
	v_mul_f32_e32 v79, s2, v79
	v_mul_f32_e32 v78, s3, v78
	v_mul_f32_e32 v80, s4, v80
	v_mul_f32_e32 v82, s5, v82
	ds_read_b32 v107, v215 offset:28672
	ds_read_b32 v102, v215 offset:28928
	ds_read_b32 v103, v215 offset:29184
	ds_read_b32 v104, v215 offset:29440
	ds_read_b32 v108, v215 offset:29696
	ds_read_b32 v100, v215 offset:29952
	ds_read_b32 v99, v215 offset:30208
	ds_read_b32 v97, v215 offset:30464
	s_waitcnt lgkmcnt(8)
	v_readlane_b32 s2, v213, 32
	v_readlane_b32 s3, v213, 33
	v_readlane_b32 s4, v213, 34
	v_readlane_b32 s5, v213, 35
	v_mul_f32_e32 v89, s2, v89
	v_mul_f32_e32 v85, s3, v85
	v_mul_f32_e32 v87, s4, v87
	v_mul_f32_e32 v90, s5, v90
	v_readlane_b32 s2, v213, 36
	v_readlane_b32 s3, v213, 37
	v_readlane_b32 s4, v213, 38
	v_readlane_b32 s5, v213, 39
	v_mul_f32_e32 v105, s2, v105
	v_mul_f32_e32 v93, s3, v93
	v_mul_f32_e32 v96, s4, v96
	v_mul_f32_e32 v98, s5, v98
	ds_read_b32 v106, v215 offset:30720
	ds_read_b32 v92, v215 offset:30976
	ds_read_b32 v91, v215 offset:31232
	ds_read_b32 v88, v215 offset:31488
	ds_read_b32 v101, v215 offset:31744
	ds_read_b32 v84, v215 offset:32000
	ds_read_b32 v83, v215 offset:32256
	ds_read_b32 v81, v215 offset:32512
	s_waitcnt lgkmcnt(8)
	v_readlane_b32 s2, v213, 40
	v_readlane_b32 s3, v213, 41
	v_readlane_b32 s4, v213, 42
	v_readlane_b32 s5, v213, 43
	v_mul_f32_e32 v107, s2, v107
	v_mul_f32_e32 v102, s3, v102
	v_mul_f32_e32 v103, s4, v103
	v_mul_f32_e32 v104, s5, v104
	v_readlane_b32 s2, v213, 44
	v_readlane_b32 s3, v213, 45
	v_readlane_b32 s4, v213, 46
	v_readlane_b32 s5, v213, 47
	v_mul_f32_e32 v108, s2, v108
	v_mul_f32_e32 v100, s3, v100
	v_mul_f32_e32 v99, s4, v99
	v_mul_f32_e32 v97, s5, v97
	ds_read_b32 v86, v215 offset:32768
	ds_read_b32 v77, v215 offset:33024
	ds_read_b32 v75, v215 offset:33280
	ds_read_b32 v73, v215 offset:33536
	ds_read_b32 v76, v215 offset:33792
	ds_read_b32 v69, v215 offset:34048
	ds_read_b32 v68, v215 offset:34304
	ds_read_b32 v66, v215 offset:34560
	s_waitcnt lgkmcnt(8)
	v_readlane_b32 s2, v213, 48
	v_readlane_b32 s3, v213, 49
	v_readlane_b32 s4, v213, 50
	v_readlane_b32 s5, v213, 51
	v_mul_f32_e32 v106, s2, v106
	v_mul_f32_e32 v92, s3, v92
	v_mul_f32_e32 v91, s4, v91
	v_mul_f32_e32 v88, s5, v88
	v_readlane_b32 s2, v213, 52
	v_readlane_b32 s3, v213, 53
	v_readlane_b32 s4, v213, 54
	v_readlane_b32 s5, v213, 55
	v_mul_f32_e32 v101, s2, v101
	v_mul_f32_e32 v84, s3, v84
	v_mul_f32_e32 v83, s4, v83
	v_mul_f32_e32 v81, s5, v81
	s_waitcnt lgkmcnt(0)
	v_readlane_b32 s2, v213, 56
	v_readlane_b32 s3, v213, 57
	v_readlane_b32 s4, v213, 58
	v_readlane_b32 s5, v213, 59
	v_mul_f32_e32 v86, s2, v86
	v_mul_f32_e32 v77, s3, v77
	v_mul_f32_e32 v75, s4, v75
	v_mul_f32_e32 v73, s5, v73
	v_readlane_b32 s2, v213, 60
	v_readlane_b32 s3, v213, 61
	v_readlane_b32 s4, v213, 62
	v_readlane_b32 s5, v213, 63
	v_mul_f32_e32 v76, s2, v76
	v_mul_f32_e32 v69, s3, v69
	v_mul_f32_e32 v68, s4, v68
	v_mul_f32_e32 v66, s5, v66
	s_branch .Lxi_done
.Lxi_sd1:
	ds_read_b32 v41, v215 offset:34560
	ds_read_b32 v43, v215 offset:34304
	ds_read_b32 v44, v215 offset:34048
	ds_read_b32 v45, v215 offset:33792
	ds_read_b32 v46, v215 offset:33536
	ds_read_b32 v47, v215 offset:33280
	ds_read_b32 v48, v215 offset:33024
	ds_read_b32 v49, v215 offset:32768
	ds_read_b32 v50, v215 offset:32512
	ds_read_b32 v51, v215 offset:32256
	ds_read_b32 v52, v215 offset:32000
	ds_read_b32 v53, v215 offset:31744
	ds_read_b32 v54, v215 offset:31488
	ds_read_b32 v55, v215 offset:31232
	ds_read_b32 v56, v215 offset:30976
	ds_read_b32 v57, v215 offset:30720
	s_waitcnt lgkmcnt(8)
	v_readlane_b32 s2, v213, 0
	v_readlane_b32 s3, v213, 1
	v_readlane_b32 s4, v213, 2
	v_readlane_b32 s5, v213, 3
	v_mul_f32_e32 v41, s2, v41
	v_mul_f32_e32 v43, s3, v43
	v_mul_f32_e32 v44, s4, v44
	v_mul_f32_e32 v45, s5, v45
	v_readlane_b32 s2, v213, 4
	v_readlane_b32 s3, v213, 5
	v_readlane_b32 s4, v213, 6
	v_readlane_b32 s5, v213, 7
	v_mul_f32_e32 v46, s2, v46
	v_mul_f32_e32 v47, s3, v47
	v_mul_f32_e32 v48, s4, v48
	v_mul_f32_e32 v49, s5, v49
	ds_read_b32 v59, v215 offset:30464
	ds_read_b32 v60, v215 offset:30208
	ds_read_b32 v61, v215 offset:29952
	ds_read_b32 v62, v215 offset:29696
	ds_read_b32 v63, v215 offset:29440
	ds_read_b32 v64, v215 offset:29184
	ds_read_b32 v65, v215 offset:28928
	ds_read_b32 v67, v215 offset:28672
	s_waitcnt lgkmcnt(8)
	v_readlane_b32 s2, v213, 8
	v_readlane_b32 s3, v213, 9
	v_readlane_b32 s4, v213, 10
	v_readlane_b32 s5, v213, 11
	v_mul_f32_e32 v50, s2, v50
	v_mul_f32_e32 v51, s3, v51
	v_mul_f32_e32 v52, s4, v52
	v_mul_f32_e32 v53, s5, v53
	v_readlane_b32 s2, v213, 12
	v_readlane_b32 s3, v213, 13
	v_readlane_b32 s4, v213, 14
	v_readlane_b32 s5, v213, 15
	v_mul_f32_e32 v54, s2, v54
	v_mul_f32_e32 v55, s3, v55
	v_mul_f32_e32 v56, s4, v56
	v_mul_f32_e32 v57, s5, v57
	ds_read_b32 v70, v215 offset:28416
	ds_read_b32 v71, v215 offset:28160
	ds_read_b32 v72, v215 offset:27904
	ds_read_b32 v74, v215 offset:27648
	ds_read_b32 v79, v215 offset:27392
	ds_read_b32 v78, v215 offset:27136
	ds_read_b32 v80, v215 offset:26880
	ds_read_b32 v82, v215 offset:26624
	s_waitcnt lgkmcnt(8)
	v_readlane_b32 s2, v213, 16
	v_readlane_b32 s3, v213, 17
	v_readlane_b32 s4, v213, 18
	v_readlane_b32 s5, v213, 19
	v_mul_f32_e32 v59, s2, v59
	v_mul_f32_e32 v60, s3, v60
	v_mul_f32_e32 v61, s4, v61
	v_mul_f32_e32 v62, s5, v62
	v_readlane_b32 s2, v213, 20
	v_readlane_b32 s3, v213, 21
	v_readlane_b32 s4, v213, 22
	v_readlane_b32 s5, v213, 23
	v_mul_f32_e32 v63, s2, v63
	v_mul_f32_e32 v64, s3, v64
	v_mul_f32_e32 v65, s4, v65
	v_mul_f32_e32 v67, s5, v67
	ds_read_b32 v89, v215 offset:26368
	ds_read_b32 v85, v215 offset:26112
	ds_read_b32 v87, v215 offset:25856
	ds_read_b32 v90, v215 offset:25600
	ds_read_b32 v105, v215 offset:25344
	ds_read_b32 v93, v215 offset:25088
	ds_read_b32 v96, v215 offset:24832
	ds_read_b32 v98, v215 offset:24576
	s_waitcnt lgkmcnt(8)
	v_readlane_b32 s2, v213, 24
	v_readlane_b32 s3, v213, 25
	v_readlane_b32 s4, v213, 26
	v_readlane_b32 s5, v213, 27
	v_mul_f32_e32 v70, s2, v70
	v_mul_f32_e32 v71, s3, v71
	v_mul_f32_e32 v72, s4, v72
	v_mul_f32_e32 v74, s5, v74
	v_readlane_b32 s2, v213, 28
	v_readlane_b32 s3, v213, 29
	v_readlane_b32 s4, v213, 30
	v_readlane_b32 s5, v213, 31
	v_mul_f32_e32 v79, s2, v79
	v_mul_f32_e32 v78, s3, v78
	v_mul_f32_e32 v80, s4, v80
	v_mul_f32_e32 v82, s5, v82
	ds_read_b32 v107, v215 offset:24320
	ds_read_b32 v102, v215 offset:24064
	ds_read_b32 v103, v215 offset:23808
	ds_read_b32 v104, v215 offset:23552
	ds_read_b32 v108, v215 offset:23296
	ds_read_b32 v100, v215 offset:23040
	ds_read_b32 v99, v215 offset:22784
	ds_read_b32 v97, v215 offset:22528
	s_waitcnt lgkmcnt(8)
	v_readlane_b32 s2, v213, 32
	v_readlane_b32 s3, v213, 33
	v_readlane_b32 s4, v213, 34
	v_readlane_b32 s5, v213, 35
	v_mul_f32_e32 v89, s2, v89
	v_mul_f32_e32 v85, s3, v85
	v_mul_f32_e32 v87, s4, v87
	v_mul_f32_e32 v90, s5, v90
	v_readlane_b32 s2, v213, 36
	v_readlane_b32 s3, v213, 37
	v_readlane_b32 s4, v213, 38
	v_readlane_b32 s5, v213, 39
	v_mul_f32_e32 v105, s2, v105
	v_mul_f32_e32 v93, s3, v93
	v_mul_f32_e32 v96, s4, v96
	v_mul_f32_e32 v98, s5, v98
	ds_read_b32 v106, v215 offset:22272
	ds_read_b32 v92, v215 offset:22016
	ds_read_b32 v91, v215 offset:21760
	ds_read_b32 v88, v215 offset:21504
	ds_read_b32 v101, v215 offset:21248
	ds_read_b32 v84, v215 offset:20992
	ds_read_b32 v83, v215 offset:20736
	ds_read_b32 v81, v215 offset:20480
	s_waitcnt lgkmcnt(8)
	v_readlane_b32 s2, v213, 40
	v_readlane_b32 s3, v213, 41
	v_readlane_b32 s4, v213, 42
	v_readlane_b32 s5, v213, 43
	v_mul_f32_e32 v107, s2, v107
	v_mul_f32_e32 v102, s3, v102
	v_mul_f32_e32 v103, s4, v103
	v_mul_f32_e32 v104, s5, v104
	v_readlane_b32 s2, v213, 44
	v_readlane_b32 s3, v213, 45
	v_readlane_b32 s4, v213, 46
	v_readlane_b32 s5, v213, 47
	v_mul_f32_e32 v108, s2, v108
	v_mul_f32_e32 v100, s3, v100
	v_mul_f32_e32 v99, s4, v99
	v_mul_f32_e32 v97, s5, v97
	ds_read_b32 v86, v215 offset:20224
	ds_read_b32 v77, v215 offset:19968
	ds_read_b32 v75, v215 offset:19712
	ds_read_b32 v73, v215 offset:19456
	ds_read_b32 v76, v215 offset:19200
	ds_read_b32 v69, v215 offset:18944
	ds_read_b32 v68, v215 offset:18688
	ds_read_b32 v66, v215 offset:18432
	s_waitcnt lgkmcnt(8)
	v_readlane_b32 s2, v213, 48
	v_readlane_b32 s3, v213, 49
	v_readlane_b32 s4, v213, 50
	v_readlane_b32 s5, v213, 51
	v_mul_f32_e32 v106, s2, v106
	v_mul_f32_e32 v92, s3, v92
	v_mul_f32_e32 v91, s4, v91
	v_mul_f32_e32 v88, s5, v88
	v_readlane_b32 s2, v213, 52
	v_readlane_b32 s3, v213, 53
	v_readlane_b32 s4, v213, 54
	v_readlane_b32 s5, v213, 55
	v_mul_f32_e32 v101, s2, v101
	v_mul_f32_e32 v84, s3, v84
	v_mul_f32_e32 v83, s4, v83
	v_mul_f32_e32 v81, s5, v81
	s_waitcnt lgkmcnt(0)
	v_readlane_b32 s2, v213, 56
	v_readlane_b32 s3, v213, 57
	v_readlane_b32 s4, v213, 58
	v_readlane_b32 s5, v213, 59
	v_mul_f32_e32 v86, s2, v86
	v_mul_f32_e32 v77, s3, v77
	v_mul_f32_e32 v75, s4, v75
	v_mul_f32_e32 v73, s5, v73
	v_readlane_b32 s2, v213, 60
	v_readlane_b32 s3, v213, 61
	v_readlane_b32 s4, v213, 62
	v_readlane_b32 s5, v213, 63
	v_mul_f32_e32 v76, s2, v76
	v_mul_f32_e32 v69, s3, v69
	v_mul_f32_e32 v68, s4, v68
	v_mul_f32_e32 v66, s5, v66
.Lxi_done:
	v_lshrrev_b32_e32 v58, 4, v94
	v_lshl_or_b32 v109, v58, 2, v0
	v_lshl_add_u32 v112, v40, 2, v95
	v_cmp_ge_u32_e64 s[2:3], v109, v40
	v_mov_b32_e32 v0, 0
	v_lshl_add_u32 v110, v109, 2, v95
	v_mov_b32_e32 v113, 0
	s_barrier
	s_and_saveexec_b64 s[4:5], s[2:3]
	s_cbranch_execz .LBB0_990
	ds_read_b32 v111, v110 offset:52224
	ds_read_b32 v113, v112 offset:52224
	s_waitcnt lgkmcnt(0)
	v_sub_f32_e32 v111, v111, v113
	v_mul_f32_e32 v111, 0x3fb8aa3b, v111
	v_exp_f32_e32 v113, v111

.LBB0_1242:
	v_lshl_add_u64 v[66:67], v[114:115], 0, v[108:109]
	s_mov_b32 s1, 0x2c84000
	v_add_co_u32_e32 v58, vcc, s1, v66
	v_lshl_add_u64 v[70:71], v[112:113], 0, v[108:109]
	s_nop 0
	v_addc_co_u32_e32 v59, vcc, 0, v67, vcc
	s_mov_b32 s1, 0x3d80000
	v_add_co_u32_e32 v62, vcc, s1, v70
	s_mov_b32 s1, 0x2c86000
	s_nop 0
	v_addc_co_u32_e32 v63, vcc, 0, v71, vcc
	v_add_co_u32_e32 v66, vcc, s1, v66
	s_mov_b32 s1, 0x3dc4000
	s_nop 0
	v_addc_co_u32_e32 v67, vcc, 0, v67, vcc
	v_add_co_u32_e32 v70, vcc, s1, v70
	global_load_dwordx4 v[58:61], v[58:59], off
	s_nop 0
	v_addc_co_u32_e32 v71, vcc, 0, v71, vcc
	global_load_dwordx4 v[62:65], v[62:63], off offset:128
	s_and_b32 s1, 1, s0
	global_load_dwordx4 v[66:69], v[66:67], off
	s_cselect_b32 s2, 0, 0x4400
	global_load_dwordx4 v[70:73], v[70:71], off offset:128
	v_add_u32_e32 v133, s2, v150
	s_setprio 1
	v_add_u32_e32 v86, v133, v126
	v_add_u32_e32 v102, v86, v127
	ds_read_b128 v[74:77], v102
	ds_read_b128 v[82:85], v102 offset:2048
	v_add_u32_e32 v103, v86, v130
	ds_read_b128 v[86:89], v103
	ds_read_b128 v[98:101], v103 offset:2048
	s_waitcnt lgkmcnt(0)
	v_mfma_f32_16x16x32_bf16 v[78:81], v[74:77], v[46:49], 0
	v_mfma_f32_16x16x32_bf16 v[74:77], v[74:77], v[50:53], 0
	v_mfma_f32_16x16x32_bf16 v[94:97], v[86:89], v[42:45], v[78:81]
	v_mfma_f32_16x16x32_bf16 v[78:81], v[86:89], v[54:57], v[74:77]
	v_mfma_f32_16x16x32_bf16 v[74:77], v[82:85], v[46:49], 0
	v_mfma_f32_16x16x32_bf16 v[90:93], v[98:101], v[42:45], v[74:77]
	v_mfma_f32_16x16x32_bf16 v[74:77], v[82:85], v[50:53], 0
	ds_read_b128 v[82:85], v102 offset:4096
	ds_read_b128 v[134:137], v102 offset:6144
	v_mfma_f32_16x16x32_bf16 v[74:77], v[98:101], v[54:57], v[74:77]
	ds_read_b128 v[98:101], v103 offset:4096
	ds_read_b128 v[138:141], v103 offset:6144
	s_waitcnt lgkmcnt(0)
	v_mfma_f32_16x16x32_bf16 v[86:89], v[82:85], v[46:49], 0
	v_mfma_f32_16x16x32_bf16 v[82:85], v[82:85], v[50:53], 0
	v_mfma_f32_16x16x32_bf16 v[102:105], v[98:101], v[42:45], v[86:89]
	v_mfma_f32_16x16x32_bf16 v[86:89], v[98:101], v[54:57], v[82:85]
	v_mfma_f32_16x16x32_bf16 v[82:85], v[134:137], v[46:49], 0
	v_mfma_f32_16x16x32_bf16 v[98:101], v[138:141], v[42:45], v[82:85]
	v_mfma_f32_16x16x32_bf16 v[82:85], v[134:137], v[50:53], 0
	v_mfma_f32_16x16x32_bf16 v[82:85], v[138:141], v[54:57], v[82:85]
	s_setprio 0
	v_max_f32_e32 v110, v95, v95
	v_max_f32_e32 v111, v94, v94
	v_max_f32_e32 v110, v111, v110
	v_max_f32_e32 v111, v97, v97
	v_max_f32_e32 v118, v96, v96
	v_max_f32_e32 v111, v118, v111
	v_max_f32_e32 v118, v93, v93
	v_max_f32_e32 v119, v92, v92
	v_max_f32_e32 v118, v119, v118
	v_max3_f32 v118, v90, v91, v118
	v_max3_f32 v110, v110, v111, v118
	v_max_f32_e32 v111, v105, v105
	v_max_f32_e32 v118, v104, v104
	v_max_f32_e32 v111, v118, v111
	v_max_f32_e32 v118, v101, v101
	v_max_f32_e32 v119, v100, v100
	v_max_f32_e32 v118, v119, v118
	v_max3_f32 v111, v102, v103, v111
	v_max3_f32 v118, v98, v99, v118
	v_max3_f32 v110, v110, v111, v118
	v_mov_b32_e32 v111, v110
	s_nop 1
	v_permlane16_swap_b32_e32 v111, v110
	v_max_f32_e32 v110, v110, v111
	v_mov_b32_e32 v111, v110
	s_nop 1
	v_permlane32_swap_b32_e32 v111, v110
	v_max_f32_e32 v110, v110, v111
	v_add_f32_e32 v111, 0x41000000, v116
	v_cmp_gt_f32_e32 vcc, v110, v111
	s_cbranch_vccz .LBB0_1244
	v_max_f32_e32 v110, v110, v110
	v_max_f32_e32 v111, v116, v116
	v_max_f32_e32 v118, v111, v110
	v_sub_f32_e32 v110, v116, v118
	v_exp_f32_e32 v110, v110
	v_mov_b32_e32 v119, v117
	v_mov_b32_e32 v116, v118
	v_pk_mul_f32 v[6:7], v[6:7], v[110:111] op_sel_hi:[1,0]
	v_pk_mul_f32 v[8:9], v[8:9], v[110:111] op_sel_hi:[1,0]
	v_pk_mul_f32 v[40:41], v[40:41], v[110:111] op_sel_hi:[1,0]
	v_pk_mul_f32 v[38:39], v[38:39], v[110:111] op_sel_hi:[1,0]
	v_pk_mul_f32 v[32:33], v[32:33], v[110:111] op_sel_hi:[1,0]
	v_pk_mul_f32 v[30:31], v[30:31], v[110:111] op_sel_hi:[1,0]
	v_pk_mul_f32 v[20:21], v[20:21], v[110:111] op_sel_hi:[1,0]
	v_pk_mul_f32 v[18:19], v[18:19], v[110:111] op_sel_hi:[1,0]
	v_pk_mul_f32 v[16:17], v[16:17], v[110:111] op_sel_hi:[1,0]
	v_pk_mul_f32 v[14:15], v[14:15], v[110:111] op_sel_hi:[1,0]
	s_branch .LBB0_1245

.LBB0_1245:
	v_max_f32_e32 v110, v79, v79
	v_max_f32_e32 v111, v78, v78
	v_max_f32_e32 v110, v111, v110
	v_max_f32_e32 v111, v81, v81
	v_max_f32_e32 v117, v80, v80
	v_max_f32_e32 v111, v117, v111
	v_max_f32_e32 v117, v77, v77
	v_max_f32_e32 v134, v76, v76
	v_max_f32_e32 v117, v134, v117
	v_max3_f32 v117, v74, v75, v117
	v_max3_f32 v110, v110, v111, v117
	v_max_f32_e32 v111, v89, v89
	v_max_f32_e32 v117, v88, v88
	v_max_f32_e32 v111, v117, v111
	v_max_f32_e32 v117, v85, v85
	v_max_f32_e32 v134, v84, v84
	v_max_f32_e32 v117, v134, v117
	v_max3_f32 v111, v86, v87, v111
	v_max3_f32 v117, v82, v83, v117
	v_max3_f32 v110, v110, v111, v117
	v_mov_b32_e32 v111, v110
	s_nop 1
	v_permlane16_swap_b32_e32 v111, v110
	v_max_f32_e32 v110, v110, v111
	v_mov_b32_e32 v111, v110
	s_nop 1
	v_permlane32_swap_b32_e32 v111, v110
	v_max_f32_e32 v110, v110, v111
	v_add_f32_e32 v111, 0x41000000, v119
	v_cmp_gt_f32_e32 vcc, v110, v111
	s_cbranch_vccz .LBB0_1247
	v_max_f32_e32 v110, v110, v110
	v_max_f32_e32 v111, v119, v119
	v_max_f32_e32 v117, v111, v110
	v_sub_f32_e32 v110, v119, v117
	v_exp_f32_e32 v110, v110
	v_mov_b32_e32 v119, v117
	v_pk_mul_f32 v[2:3], v[2:3], v[110:111] op_sel_hi:[1,0]
	v_pk_mul_f32 v[4:5], v[4:5], v[110:111] op_sel_hi:[1,0]
	v_pk_mul_f32 v[36:37], v[36:37], v[110:111] op_sel_hi:[1,0]
	v_pk_mul_f32 v[34:35], v[34:35], v[110:111] op_sel_hi:[1,0]
	v_pk_mul_f32 v[28:29], v[28:29], v[110:111] op_sel_hi:[1,0]
	v_pk_mul_f32 v[26:27], v[26:27], v[110:111] op_sel_hi:[1,0]
	v_pk_mul_f32 v[24:25], v[24:25], v[110:111] op_sel_hi:[1,0]
	v_pk_mul_f32 v[22:23], v[22:23], v[110:111] op_sel_hi:[1,0]
	v_pk_mul_f32 v[12:13], v[12:13], v[110:111] op_sel_hi:[1,0]
	v_pk_mul_f32 v[10:11], v[10:11], v[110:111] op_sel_hi:[1,0]

.LBB0_1249:
	s_setprio 1
	v_add_u32_e32 v62, v150, v126
	v_add_u32_e32 v86, v62, v127
	ds_read_b128 v[58:61], v86 offset:17408
	v_add_u32_e32 v87, v62, v130
	ds_read_b128 v[66:69], v87 offset:17408
	s_waitcnt lgkmcnt(1)
	v_mfma_f32_16x16x32_bf16 v[62:65], v[58:61], v[46:49], 0
	v_mfma_f32_16x16x32_bf16 v[58:61], v[58:61], v[50:53], 0
	s_waitcnt lgkmcnt(0)
	v_mfma_f32_16x16x32_bf16 v[62:65], v[66:69], v[42:45], v[62:65]
	v_mfma_f32_16x16x32_bf16 v[58:61], v[66:69], v[54:57], v[58:61]
	ds_read_b128 v[66:69], v86 offset:19456
	ds_read_b128 v[70:73], v87 offset:19456
	s_waitcnt lgkmcnt(1)
	v_mfma_f32_16x16x32_bf16 v[74:77], v[66:69], v[46:49], 0
	v_mfma_f32_16x16x32_bf16 v[66:69], v[66:69], v[50:53], 0
	s_waitcnt lgkmcnt(0)
	v_mfma_f32_16x16x32_bf16 v[78:81], v[70:73], v[42:45], v[74:77]
	v_mfma_f32_16x16x32_bf16 v[70:73], v[70:73], v[54:57], v[66:69]
	s_nop 4
	ds_read_b128 v[66:69], v86 offset:21504
	ds_read_b128 v[82:85], v87 offset:21504
	s_waitcnt lgkmcnt(1)
	v_mfma_f32_16x16x32_bf16 v[74:77], v[66:69], v[46:49], 0
	v_mfma_f32_16x16x32_bf16 v[66:69], v[66:69], v[50:53], 0
	s_waitcnt lgkmcnt(0)
	v_mfma_f32_16x16x32_bf16 v[74:77], v[82:85], v[42:45], v[74:77]
	v_mfma_f32_16x16x32_bf16 v[66:69], v[82:85], v[54:57], v[66:69]
	ds_read_b128 v[82:85], v86 offset:23552
	ds_read_b128 v[86:89], v87 offset:23552
	s_waitcnt lgkmcnt(1)
	v_mfma_f32_16x16x32_bf16 v[46:49], v[82:85], v[46:49], 0
	s_waitcnt lgkmcnt(0)
	v_mfma_f32_16x16x32_bf16 v[46:49], v[86:89], v[42:45], v[46:49]
	v_mfma_f32_16x16x32_bf16 v[42:45], v[82:85], v[50:53], 0
	v_mfma_f32_16x16x32_bf16 v[42:45], v[86:89], v[54:57], v[42:45]
	s_setprio 0
	v_max_f32_e32 v50, v63, v63
	v_max_f32_e32 v51, v62, v62
	v_max_f32_e32 v50, v51, v50
	v_max_f32_e32 v51, v65, v65
	v_max_f32_e32 v52, v64, v64
	v_max_f32_e32 v51, v52, v51
	v_max_f32_e32 v52, v81, v81
	v_max_f32_e32 v53, v80, v80
	v_max_f32_e32 v52, v53, v52
	v_max3_f32 v52, v78, v79, v52
	v_max3_f32 v50, v50, v51, v52
	v_max_f32_e32 v51, v77, v77
	v_max_f32_e32 v52, v76, v76
	v_max_f32_e32 v51, v52, v51
	v_max_f32_e32 v52, v49, v49
	v_max_f32_e32 v53, v48, v48
	v_max_f32_e32 v52, v53, v52
	v_max3_f32 v51, v74, v75, v51
	v_max3_f32 v52, v46, v47, v52
	v_max3_f32 v50, v50, v51, v52
	v_mov_b32_e32 v51, v50
	s_nop 1
	v_permlane16_swap_b32_e32 v51, v50
	v_max_f32_e32 v50, v50, v51
	v_mov_b32_e32 v51, v50
	s_nop 1
	v_permlane32_swap_b32_e32 v51, v50
	v_max_f32_e32 v50, v50, v51
	v_add_f32_e32 v51, 0x41000000, v110
	v_cmp_gt_f32_e32 vcc, v50, v51
	s_cbranch_vccz .LBB0_1251
	v_max_f32_e32 v50, v50, v50
	v_max_f32_e32 v51, v110, v110
	v_max_f32_e32 v51, v51, v50
	v_sub_f32_e32 v50, v110, v51
	v_exp_f32_e32 v50, v50
	v_mov_b32_e32 v110, v51
	v_pk_mul_f32 v[6:7], v[6:7], v[50:51] op_sel_hi:[1,0]
	v_pk_mul_f32 v[8:9], v[8:9], v[50:51] op_sel_hi:[1,0]
	v_pk_mul_f32 v[40:41], v[40:41], v[50:51] op_sel_hi:[1,0]
	v_pk_mul_f32 v[38:39], v[38:39], v[50:51] op_sel_hi:[1,0]
	v_pk_mul_f32 v[32:33], v[32:33], v[50:51] op_sel_hi:[1,0]
	v_pk_mul_f32 v[30:31], v[30:31], v[50:51] op_sel_hi:[1,0]
	v_pk_mul_f32 v[20:21], v[20:21], v[50:51] op_sel_hi:[1,0]
	v_pk_mul_f32 v[18:19], v[18:19], v[50:51] op_sel_hi:[1,0]
	v_pk_mul_f32 v[16:17], v[16:17], v[50:51] op_sel_hi:[1,0]
	v_pk_mul_f32 v[14:15], v[14:15], v[50:51] op_sel_hi:[1,0]
.LBB0_1251:
	v_max_f32_e32 v50, v59, v59
	v_max_f32_e32 v51, v58, v58
	v_max_f32_e32 v50, v51, v50
	v_max_f32_e32 v51, v61, v61
	v_max_f32_e32 v52, v60, v60
	v_max_f32_e32 v51, v52, v51
	v_max_f32_e32 v52, v73, v73
	v_max_f32_e32 v53, v72, v72
	v_max_f32_e32 v52, v53, v52
	v_max3_f32 v52, v70, v71, v52
	v_max3_f32 v50, v50, v51, v52
	v_max_f32_e32 v51, v69, v69
	v_max_f32_e32 v52, v68, v68
	v_max_f32_e32 v51, v52, v51
	v_max_f32_e32 v52, v45, v45
	v_max_f32_e32 v53, v44, v44
	v_max_f32_e32 v52, v53, v52
	v_max3_f32 v51, v66, v67, v51
	v_max3_f32 v52, v42, v43, v52
	v_max3_f32 v50, v50, v51, v52
	v_mov_b32_e32 v51, v50
	s_nop 1
	v_permlane16_swap_b32_e32 v51, v50
	v_max_f32_e32 v50, v50, v51
	v_mov_b32_e32 v51, v50
	s_nop 1
	v_permlane32_swap_b32_e32 v51, v50
	v_max_f32_e32 v50, v50, v51
	v_add_f32_e32 v51, 0x41000000, v111
	v_cmp_gt_f32_e32 vcc, v50, v51
	s_cbranch_vccz .LBB0_1253
	v_max_f32_e32 v50, v50, v50
	v_max_f32_e32 v51, v111, v111
	v_max_f32_e32 v51, v51, v50
	v_sub_f32_e32 v50, v111, v51
	v_exp_f32_e32 v50, v50
	v_mov_b32_e32 v111, v51
	v_pk_mul_f32 v[2:3], v[2:3], v[50:51] op_sel_hi:[1,0]
	v_pk_mul_f32 v[4:5], v[4:5], v[50:51] op_sel_hi:[1,0]
	v_pk_mul_f32 v[36:37], v[36:37], v[50:51] op_sel_hi:[1,0]
	v_pk_mul_f32 v[34:35], v[34:35], v[50:51] op_sel_hi:[1,0]
	v_pk_mul_f32 v[28:29], v[28:29], v[50:51] op_sel_hi:[1,0]
	v_pk_mul_f32 v[26:27], v[26:27], v[50:51] op_sel_hi:[1,0]
	v_pk_mul_f32 v[24:25], v[24:25], v[50:51] op_sel_hi:[1,0]
	v_pk_mul_f32 v[22:23], v[22:23], v[50:51] op_sel_hi:[1,0]
	v_pk_mul_f32 v[12:13], v[12:13], v[50:51] op_sel_hi:[1,0]
	v_pk_mul_f32 v[10:11], v[10:11], v[50:51] op_sel_hi:[1,0]

.LBB0_1259:
	s_or_b64 exec, exec, s[4:5]
	v_max_f32_e32 v118, v95, v95
	v_max_f32_e32 v119, v94, v94
	v_max_f32_e32 v118, v119, v118
	v_max_f32_e32 v119, v97, v97
	v_max_f32_e32 v122, v96, v96
	v_max_f32_e32 v119, v122, v119
	v_max_f32_e32 v122, v93, v93
	v_max_f32_e32 v123, v92, v92
	v_max_f32_e32 v122, v123, v122
	v_max3_f32 v122, v90, v91, v122
	v_max3_f32 v118, v118, v119, v122
	v_max_f32_e32 v119, v105, v105
	v_max_f32_e32 v122, v104, v104
	v_max_f32_e32 v119, v122, v119
	v_max_f32_e32 v122, v101, v101
	v_max_f32_e32 v123, v100, v100
	v_max_f32_e32 v122, v123, v122
	v_max3_f32 v119, v102, v103, v119
	v_max3_f32 v122, v98, v99, v122
	v_max3_f32 v118, v118, v119, v122
	v_mov_b32_e32 v119, v118
	s_nop 1
	v_permlane16_swap_b32_e32 v119, v118
	v_max_f32_e32 v118, v118, v119
	v_mov_b32_e32 v119, v118
	s_nop 1
	v_permlane32_swap_b32_e32 v119, v118
	v_max_f32_e32 v118, v118, v119
	v_add_f32_e32 v119, 0x41000000, v120
	v_cmp_gt_f32_e32 vcc, v118, v119
	s_cbranch_vccz .LBB0_1266
	v_max_f32_e32 v118, v118, v118
	v_max_f32_e32 v119, v120, v120
	v_max_f32_e32 v122, v119, v118
	v_sub_f32_e32 v118, v120, v122
	v_exp_f32_e32 v118, v118
	v_mov_b32_e32 v123, v121
	v_mov_b32_e32 v120, v122
	v_pk_mul_f32 v[38:39], v[38:39], v[118:119] op_sel_hi:[1,0]
	v_pk_mul_f32 v[40:41], v[40:41], v[118:119] op_sel_hi:[1,0]
	v_pk_mul_f32 v[32:33], v[32:33], v[118:119] op_sel_hi:[1,0]
	v_pk_mul_f32 v[30:31], v[30:31], v[118:119] op_sel_hi:[1,0]
	v_pk_mul_f32 v[24:25], v[24:25], v[118:119] op_sel_hi:[1,0]
	v_pk_mul_f32 v[22:23], v[22:23], v[118:119] op_sel_hi:[1,0]
	v_pk_mul_f32 v[12:13], v[12:13], v[118:119] op_sel_hi:[1,0]
	v_pk_mul_f32 v[10:11], v[10:11], v[118:119] op_sel_hi:[1,0]
	v_pk_mul_f32 v[8:9], v[8:9], v[118:119] op_sel_hi:[1,0]
	v_pk_mul_f32 v[6:7], v[6:7], v[118:119] op_sel_hi:[1,0]
	s_and_saveexec_b64 s[4:5], s[0:1]
	s_cbranch_execz .LBB0_1262

.LBB0_1262:
	s_or_b64 exec, exec, s[4:5]
	v_max_f32_e32 v0, v79, v79
	v_max_f32_e32 v118, v78, v78
	v_max_f32_e32 v0, v118, v0
	v_max_f32_e32 v118, v81, v81
	v_max_f32_e32 v119, v80, v80
	v_max_f32_e32 v118, v119, v118
	v_max_f32_e32 v119, v77, v77
	v_max_f32_e32 v121, v76, v76
	v_max_f32_e32 v119, v121, v119
	v_max3_f32 v119, v74, v75, v119
	v_max3_f32 v0, v0, v118, v119
	v_max_f32_e32 v118, v89, v89
	v_max_f32_e32 v119, v88, v88
	v_max_f32_e32 v118, v119, v118
	v_max_f32_e32 v119, v85, v85
	v_max_f32_e32 v121, v84, v84
	v_max_f32_e32 v119, v121, v119
	v_max3_f32 v118, v86, v87, v118
	v_max3_f32 v119, v82, v83, v119
	v_max3_f32 v0, v0, v118, v119
	v_mov_b32_e32 v118, v0
	s_nop 1
	v_permlane16_swap_b32_e32 v118, v0
	v_max_f32_e32 v0, v0, v118
	v_mov_b32_e32 v118, v0
	s_nop 1
	v_permlane32_swap_b32_e32 v118, v0
	v_max_f32_e32 v0, v0, v118
	v_add_f32_e32 v118, 0x41000000, v123
	v_cmp_gt_f32_e32 vcc, v0, v118
	s_cbranch_vccz .LBB0_1264
	v_max_f32_e32 v0, v0, v0
	v_max_f32_e32 v118, v123, v123
	v_max_f32_e32 v121, v118, v0
	v_sub_f32_e32 v0, v123, v121
	v_exp_f32_e32 v0, v0
	v_mov_b32_e32 v123, v121
	v_pk_mul_f32 v[34:35], v[34:35], v[0:1] op_sel_hi:[1,0]
	v_pk_mul_f32 v[36:37], v[36:37], v[0:1] op_sel_hi:[1,0]
	v_pk_mul_f32 v[28:29], v[28:29], v[0:1] op_sel_hi:[1,0]
	v_pk_mul_f32 v[26:27], v[26:27], v[0:1] op_sel_hi:[1,0]
	v_pk_mul_f32 v[20:21], v[20:21], v[0:1] op_sel_hi:[1,0]
	v_pk_mul_f32 v[18:19], v[18:19], v[0:1] op_sel_hi:[1,0]
	v_pk_mul_f32 v[16:17], v[16:17], v[0:1] op_sel_hi:[1,0]
	v_pk_mul_f32 v[14:15], v[14:15], v[0:1] op_sel_hi:[1,0]
	v_pk_mul_f32 v[4:5], v[4:5], v[0:1] op_sel_hi:[1,0]
	v_pk_mul_f32 v[2:3], v[2:3], v[0:1] op_sel_hi:[1,0]

.LBB0_1267:
	v_cmp_gt_u32_e64 s[0:1], 62, v146
	v_min_u32_e32 v0, 61, v146
	s_setprio 1
	v_add_u32_e32 v62, v150, v167
	v_add_u32_e32 v86, v62, v171
	ds_read_b128 v[58:61], v86
	v_add_u32_e32 v87, v62, v172
	ds_read_b128 v[62:65], v87
	s_waitcnt lgkmcnt(1)
	v_mfma_f32_16x16x32_bf16 v[66:69], v[58:61], v[46:49], 0
	v_mfma_f32_16x16x32_bf16 v[58:61], v[58:61], v[50:53], 0
	s_waitcnt lgkmcnt(0)
	v_mfma_f32_16x16x32_bf16 v[74:77], v[62:65], v[42:45], v[66:69]
	v_mfma_f32_16x16x32_bf16 v[58:61], v[62:65], v[54:57], v[58:61]
	ds_read_b128 v[62:65], v86 offset:2048
	s_nop 2
	ds_read_b128 v[66:69], v87 offset:2048
	s_waitcnt lgkmcnt(1)
	v_mfma_f32_16x16x32_bf16 v[70:73], v[62:65], v[46:49], 0
	v_mfma_f32_16x16x32_bf16 v[62:65], v[62:65], v[50:53], 0
	s_waitcnt lgkmcnt(0)
	v_mfma_f32_16x16x32_bf16 v[78:81], v[66:69], v[42:45], v[70:73]
	v_mfma_f32_16x16x32_bf16 v[62:65], v[66:69], v[54:57], v[62:65]
	ds_read_b128 v[66:69], v86 offset:4096
	s_nop 2
	ds_read_b128 v[70:73], v87 offset:4096
	s_waitcnt lgkmcnt(1)
	v_mfma_f32_16x16x32_bf16 v[82:85], v[66:69], v[46:49], 0
	v_mfma_f32_16x16x32_bf16 v[66:69], v[66:69], v[50:53], 0
	s_waitcnt lgkmcnt(0)
	v_mfma_f32_16x16x32_bf16 v[82:85], v[70:73], v[42:45], v[82:85]
	v_mfma_f32_16x16x32_bf16 v[66:69], v[70:73], v[54:57], v[66:69]
	ds_read_b128 v[70:73], v86 offset:6144
	ds_read_b128 v[86:89], v87 offset:6144
	s_waitcnt lgkmcnt(1)
	v_mfma_f32_16x16x32_bf16 v[46:49], v[70:73], v[46:49], 0
	s_waitcnt lgkmcnt(0)
	v_mfma_f32_16x16x32_bf16 v[46:49], v[86:89], v[42:45], v[46:49]
	v_mfma_f32_16x16x32_bf16 v[42:45], v[70:73], v[50:53], 0
	v_mfma_f32_16x16x32_bf16 v[42:45], v[86:89], v[54:57], v[42:45]
	s_setprio 0
	v_lshlrev_b32_e32 v0, 6, v0
	v_sub_u32_e32 v73, 0xfffffe80, v0
	v_add_u32_e32 v0, v164, v73
	v_cmp_gt_u32_e32 vcc, s51, v0
	v_add_u32_e32 v0, v162, v73
	v_cmp_gt_u32_e64 s[2:3], s51, v0
	v_add_u32_e32 v0, v161, v73
	v_cmp_gt_u32_e64 s[4:5], s51, v0
	v_add_u32_e32 v0, v160, v73
	v_cmp_gt_u32_e64 s[6:7], s51, v0
	s_and_b64 s[6:7], s[6:7], s[0:1]
	s_and_b64 s[4:5], s[4:5], s[0:1]
	s_and_b64 s[2:3], s[2:3], s[0:1]
	s_and_b64 vcc, vcc, s[0:1]
	v_cndmask_b32_e64 v0, v125, v46, s[6:7]
	v_cndmask_b32_e64 v46, v125, v47, s[4:5]
	v_cndmask_b32_e64 v47, v125, v48, s[2:3]
	v_cndmask_b32_e32 v48, v125, v49, vcc
	v_add_u32_e32 v49, v159, v73
	v_cmp_gt_u32_e32 vcc, s51, v49
	v_add_u32_e32 v49, v158, v73
	v_cmp_gt_u32_e64 s[2:3], s51, v49
	v_add_u32_e32 v49, v157, v73
	s_and_b64 vcc, vcc, s[0:1]
	v_add_u32_e32 v53, v155, v73
	v_cmp_gt_u32_e64 s[4:5], s51, v49
	s_and_b64 s[2:3], s[2:3], s[0:1]
	v_cndmask_b32_e32 v52, v125, v85, vcc
	v_cmp_gt_u32_e32 vcc, s51, v53
	v_add_u32_e32 v53, v154, v73
	v_add_u32_e32 v49, v156, v73
	s_and_b64 s[4:5], s[4:5], s[0:1]
	v_cndmask_b32_e64 v51, v125, v84, s[2:3]
	v_cmp_gt_u32_e64 s[2:3], s51, v53
	v_add_u32_e32 v53, v153, v73
	s_and_b64 vcc, vcc, s[0:1]
	v_add_u32_e32 v57, v151, v73
	v_cmp_gt_u32_e64 s[6:7], s51, v49
	v_cndmask_b32_e64 v50, v125, v83, s[4:5]
	v_cmp_gt_u32_e64 s[4:5], s51, v53
	s_and_b64 s[2:3], s[2:3], s[0:1]
	v_cndmask_b32_e32 v56, v125, v81, vcc
	v_cmp_gt_u32_e32 vcc, s51, v57
	v_add_u32_e32 v57, v147, v73
	s_and_b64 s[6:7], s[6:7], s[0:1]
	v_add_u32_e32 v53, v152, v73
	s_and_b64 s[4:5], s[4:5], s[0:1]
	v_cndmask_b32_e64 v55, v125, v80, s[2:3]
	v_cmp_gt_u32_e64 s[2:3], s51, v57
	v_add_u32_e32 v57, v144, v73
	v_cndmask_b32_e64 v49, v125, v82, s[6:7]
	v_cmp_gt_u32_e64 s[6:7], s51, v53
	v_cndmask_b32_e64 v54, v125, v79, s[4:5]
	v_sub_u32_e32 v57, v113, v57
	s_movk_i32 s4, 0xfefe
	s_and_b64 s[6:7], s[6:7], s[0:1]
	v_cmp_lt_u32_e64 s[4:5], s4, v57
	v_add_u32_e32 v57, v145, v73
	v_cndmask_b32_e64 v53, v125, v78, s[6:7]
	v_cmp_gt_u32_e64 s[6:7], s51, v57
	s_and_b64 s[6:7], s[6:7], s[0:1]
	s_and_b64 s[4:5], s[4:5], s[0:1]
	v_cndmask_b32_e64 v57, v125, v74, s[6:7]
	v_cndmask_b32_e64 v70, v125, v75, s[4:5]
	s_and_b64 s[2:3], s[2:3], s[0:1]
	s_and_b64 vcc, vcc, s[0:1]
	v_cndmask_b32_e64 v71, v125, v76, s[2:3]
	v_cndmask_b32_e32 v72, v125, v77, vcc
	v_max_f32_e32 v74, v57, v57
	v_max_f32_e32 v75, v70, v70
	v_max_f32_e32 v74, v74, v75
	v_max_f32_e32 v75, v72, v72
	v_max_f32_e32 v76, v71, v71
	v_max_f32_e32 v75, v76, v75
	v_max_f32_e32 v76, v56, v56
	v_max_f32_e32 v77, v55, v55
	v_max_f32_e32 v76, v77, v76
	v_max3_f32 v76, v53, v54, v76
	v_max3_f32 v74, v74, v75, v76
	v_max_f32_e32 v75, v52, v52
	v_max_f32_e32 v76, v51, v51
	v_max_f32_e32 v75, v76, v75
	v_max_f32_e32 v76, v48, v48
	v_max_f32_e32 v77, v47, v47
	v_max_f32_e32 v76, v77, v76
	v_max3_f32 v75, v49, v50, v75
	v_max3_f32 v76, v0, v46, v76
	v_max3_f32 v74, v74, v75, v76
	v_mov_b32_e32 v75, v74
	s_nop 1
	v_permlane16_swap_b32_e32 v75, v74
	v_max_f32_e32 v74, v74, v75
	v_mov_b32_e32 v75, v74
	s_nop 1
	v_permlane32_swap_b32_e32 v75, v74
	v_max_f32_e32 v74, v74, v75
	v_add_f32_e32 v75, 0x41000000, v118
	v_cmp_gt_f32_e32 vcc, v74, v75
	s_cbranch_vccz .LBB0_1269
	v_max_f32_e32 v74, v74, v74
	v_max_f32_e32 v75, v118, v118
	v_max_f32_e32 v75, v75, v74
	v_sub_f32_e32 v74, v118, v75
	v_exp_f32_e32 v74, v74
	v_mov_b32_e32 v118, v75
	v_pk_mul_f32 v[38:39], v[38:39], v[74:75] op_sel_hi:[1,0]
	v_pk_mul_f32 v[40:41], v[40:41], v[74:75] op_sel_hi:[1,0]
	v_pk_mul_f32 v[32:33], v[32:33], v[74:75] op_sel_hi:[1,0]
	v_pk_mul_f32 v[30:31], v[30:31], v[74:75] op_sel_hi:[1,0]
	v_pk_mul_f32 v[24:25], v[24:25], v[74:75] op_sel_hi:[1,0]
	v_pk_mul_f32 v[22:23], v[22:23], v[74:75] op_sel_hi:[1,0]
	v_pk_mul_f32 v[12:13], v[12:13], v[74:75] op_sel_hi:[1,0]
	v_pk_mul_f32 v[10:11], v[10:11], v[74:75] op_sel_hi:[1,0]
	v_pk_mul_f32 v[8:9], v[8:9], v[74:75] op_sel_hi:[1,0]
	v_pk_mul_f32 v[6:7], v[6:7], v[74:75] op_sel_hi:[1,0]
.LBB0_1269:
	v_add_u32_e32 v74, v143, v73
	v_cmp_gt_u32_e32 vcc, s51, v74
	v_add_u32_e32 v74, v142, v73
	v_cmp_gt_u32_e64 s[2:3], s51, v74
	v_add_u32_e32 v74, v141, v73
	v_cmp_gt_u32_e64 s[4:5], s51, v74
	v_add_u32_e32 v74, v140, v73
	v_cmp_gt_u32_e64 s[6:7], s51, v74
	s_and_b64 vcc, vcc, s[0:1]
	v_add_u32_e32 v74, v139, v73
	s_and_b64 s[2:3], s[2:3], s[0:1]
	v_cndmask_b32_e32 v45, v125, v45, vcc
	v_cmp_gt_u32_e32 vcc, s51, v74
	v_add_u32_e32 v74, v138, v73
	s_and_b64 s[4:5], s[4:5], s[0:1]
	v_cndmask_b32_e64 v44, v125, v44, s[2:3]
	v_cmp_gt_u32_e64 s[2:3], s51, v74
	v_add_u32_e32 v74, v137, v73
	s_and_b64 s[6:7], s[6:7], s[0:1]
	v_cndmask_b32_e64 v43, v125, v43, s[4:5]
	v_cmp_gt_u32_e64 s[4:5], s51, v74
	v_add_u32_e32 v74, v136, v73
	v_cndmask_b32_e64 v42, v125, v42, s[6:7]
	v_cmp_gt_u32_e64 s[6:7], s51, v74
	s_and_b64 vcc, vcc, s[0:1]
	v_add_u32_e32 v74, v135, v73
	s_and_b64 s[2:3], s[2:3], s[0:1]
	v_cndmask_b32_e32 v69, v125, v69, vcc
	v_cmp_gt_u32_e32 vcc, s51, v74
	v_add_u32_e32 v74, v134, v73
	s_and_b64 s[4:5], s[4:5], s[0:1]
	v_cndmask_b32_e64 v68, v125, v68, s[2:3]
	v_cmp_gt_u32_e64 s[2:3], s51, v74
	v_add_u32_e32 v74, v133, v73
	s_and_b64 s[6:7], s[6:7], s[0:1]
	v_cndmask_b32_e64 v67, v125, v67, s[4:5]
	v_cmp_gt_u32_e64 s[4:5], s51, v74
	v_add_u32_e32 v74, v132, v73
	v_cndmask_b32_e64 v66, v125, v66, s[6:7]
	v_cmp_gt_u32_e64 s[6:7], s51, v74
	s_and_b64 vcc, vcc, s[0:1]
	v_add_u32_e32 v74, v131, v73
	s_and_b64 s[2:3], s[2:3], s[0:1]
	v_cndmask_b32_e32 v65, v125, v65, vcc
	v_cmp_gt_u32_e32 vcc, s51, v74
	v_add_u32_e32 v74, v130, v73
	s_and_b64 s[4:5], s[4:5], s[0:1]
	v_cndmask_b32_e64 v64, v125, v64, s[2:3]
	v_cmp_gt_u32_e64 s[2:3], s51, v74
	v_add_u32_e32 v74, v128, v73
	s_and_b64 s[6:7], s[6:7], s[0:1]
	v_cndmask_b32_e64 v63, v125, v63, s[4:5]
	v_sub_u32_e32 v74, v113, v74
	s_movk_i32 s4, 0xfefe
	v_add_u32_e32 v73, v129, v73
	v_cndmask_b32_e64 v62, v125, v62, s[6:7]
	v_cmp_lt_u32_e64 s[4:5], s4, v74
	v_cmp_gt_u32_e64 s[6:7], s51, v73
	s_and_b64 s[6:7], s[6:7], s[0:1]
	s_and_b64 s[4:5], s[4:5], s[0:1]
	v_cndmask_b32_e64 v58, v125, v58, s[6:7]
	v_cndmask_b32_e64 v59, v125, v59, s[4:5]
	s_and_b64 s[2:3], s[2:3], s[0:1]
	s_and_b64 vcc, vcc, s[0:1]
	v_cndmask_b32_e64 v60, v125, v60, s[2:3]
	v_cndmask_b32_e32 v61, v125, v61, vcc
	v_max_f32_e32 v73, v58, v58
	v_max_f32_e32 v74, v59, v59
	v_max_f32_e32 v73, v73, v74
	v_max_f32_e32 v74, v61, v61
	v_max_f32_e32 v75, v60, v60
	v_max_f32_e32 v74, v75, v74
	v_max_f32_e32 v75, v65, v65
	v_max_f32_e32 v76, v64, v64
	v_max_f32_e32 v75, v76, v75
	v_max3_f32 v75, v62, v63, v75
	v_max3_f32 v73, v73, v74, v75
	v_max_f32_e32 v74, v69, v69
	v_max_f32_e32 v75, v68, v68
	v_max_f32_e32 v74, v75, v74
	v_max_f32_e32 v75, v45, v45
	v_max_f32_e32 v76, v44, v44
	v_max_f32_e32 v75, v76, v75
	v_max3_f32 v74, v66, v67, v74
	v_max3_f32 v75, v42, v43, v75
	v_max3_f32 v73, v73, v74, v75
	v_mov_b32_e32 v74, v73
	s_nop 1
	v_permlane16_swap_b32_e32 v74, v73
	v_max_f32_e32 v73, v73, v74
	v_mov_b32_e32 v74, v73
	s_nop 1
	v_permlane32_swap_b32_e32 v74, v73
	v_max_f32_e32 v73, v73, v74
	v_add_f32_e32 v74, 0x41000000, v119
	v_cmp_gt_f32_e32 vcc, v73, v74
	s_cbranch_vccz .LBB0_1271
	v_max_f32_e32 v73, v73, v73
	v_max_f32_e32 v74, v119, v119
	v_max_f32_e32 v73, v74, v73
	v_sub_f32_e32 v74, v119, v73
	v_exp_f32_e32 v74, v74
	v_mov_b32_e32 v119, v73
	v_pk_mul_f32 v[34:35], v[34:35], v[74:75] op_sel_hi:[1,0]
	v_pk_mul_f32 v[36:37], v[36:37], v[74:75] op_sel_hi:[1,0]
	v_pk_mul_f32 v[28:29], v[28:29], v[74:75] op_sel_hi:[1,0]
	v_pk_mul_f32 v[26:27], v[26:27], v[74:75] op_sel_hi:[1,0]
	v_pk_mul_f32 v[20:21], v[20:21], v[74:75] op_sel_hi:[1,0]
	v_pk_mul_f32 v[18:19], v[18:19], v[74:75] op_sel_hi:[1,0]
	v_pk_mul_f32 v[16:17], v[16:17], v[74:75] op_sel_hi:[1,0]
	v_pk_mul_f32 v[14:15], v[14:15], v[74:75] op_sel_hi:[1,0]
	v_pk_mul_f32 v[4:5], v[4:5], v[74:75] op_sel_hi:[1,0]
	v_pk_mul_f32 v[2:3], v[2:3], v[74:75] op_sel_hi:[1,0]

.LBB0_1282:
	s_waitcnt vmcnt(0)
	s_setprio 1
	v_add_u32_e32 v0, v150, v115
	v_add_u32_e32 v86, v0, v130
	ds_read_b128 v[58:61], v86 offset:17408
	v_add_u32_e32 v0, v0, v129
	ds_read_b128 v[66:69], v0 offset:17408
	s_waitcnt lgkmcnt(1)
	v_mfma_f32_16x16x32_bf16 v[62:65], v[58:61], v[46:49], 0
	v_mfma_f32_16x16x32_bf16 v[58:61], v[58:61], v[50:53], 0
	s_waitcnt lgkmcnt(0)
	v_mfma_f32_16x16x32_bf16 v[62:65], v[66:69], v[42:45], v[62:65]
	v_mfma_f32_16x16x32_bf16 v[58:61], v[66:69], v[54:57], v[58:61]
	ds_read_b128 v[66:69], v86 offset:19456
	ds_read_b128 v[70:73], v0 offset:19456
	s_waitcnt lgkmcnt(1)
	v_mfma_f32_16x16x32_bf16 v[74:77], v[66:69], v[46:49], 0
	v_mfma_f32_16x16x32_bf16 v[66:69], v[66:69], v[50:53], 0
	s_waitcnt lgkmcnt(0)
	v_mfma_f32_16x16x32_bf16 v[78:81], v[70:73], v[42:45], v[74:77]
	v_mfma_f32_16x16x32_bf16 v[70:73], v[70:73], v[54:57], v[66:69]
	s_nop 4
	ds_read_b128 v[66:69], v86 offset:21504
	ds_read_b128 v[82:85], v0 offset:21504
	s_waitcnt lgkmcnt(1)
	v_mfma_f32_16x16x32_bf16 v[74:77], v[66:69], v[46:49], 0
	v_mfma_f32_16x16x32_bf16 v[66:69], v[66:69], v[50:53], 0
	s_waitcnt lgkmcnt(0)
	v_mfma_f32_16x16x32_bf16 v[74:77], v[82:85], v[42:45], v[74:77]
	v_mfma_f32_16x16x32_bf16 v[66:69], v[82:85], v[54:57], v[66:69]
	ds_read_b128 v[82:85], v86 offset:23552
	ds_read_b128 v[86:89], v0 offset:23552
	s_waitcnt lgkmcnt(1)
	v_mfma_f32_16x16x32_bf16 v[46:49], v[82:85], v[46:49], 0
	s_waitcnt lgkmcnt(0)
	v_mfma_f32_16x16x32_bf16 v[46:49], v[86:89], v[42:45], v[46:49]
	v_mfma_f32_16x16x32_bf16 v[42:45], v[82:85], v[50:53], 0
	v_mfma_f32_16x16x32_bf16 v[42:45], v[86:89], v[54:57], v[42:45]
	s_setprio 0
	v_max_f32_e32 v0, v63, v63
	v_max_f32_e32 v50, v62, v62
	v_max_f32_e32 v0, v50, v0
	v_max_f32_e32 v50, v65, v65
	v_max_f32_e32 v51, v64, v64
	v_max_f32_e32 v50, v51, v50
	v_max_f32_e32 v51, v81, v81
	v_max_f32_e32 v52, v80, v80
	v_max_f32_e32 v51, v52, v51
	v_max3_f32 v51, v78, v79, v51
	v_max3_f32 v0, v0, v50, v51
	v_max_f32_e32 v50, v77, v77
	v_max_f32_e32 v51, v76, v76
	v_max_f32_e32 v50, v51, v50
	v_max_f32_e32 v51, v49, v49
	v_max_f32_e32 v52, v48, v48
	v_max_f32_e32 v51, v52, v51
	v_max3_f32 v50, v74, v75, v50
	v_max3_f32 v51, v46, v47, v51
	v_max3_f32 v0, v0, v50, v51
	v_mov_b32_e32 v50, v0
	s_nop 1
	v_permlane16_swap_b32_e32 v50, v0
	v_max_f32_e32 v0, v0, v50
	v_mov_b32_e32 v50, v0
	s_nop 1
	v_permlane32_swap_b32_e32 v50, v0
	v_max_f32_e32 v0, v0, v50
	v_add_f32_e32 v50, 0x41000000, v118
	v_cmp_gt_f32_e32 vcc, v0, v50
	s_cbranch_vccz .LBB0_1284
	v_max_f32_e32 v0, v0, v0
	v_max_f32_e32 v50, v118, v118
	v_max_f32_e32 v50, v50, v0
	v_sub_f32_e32 v0, v118, v50
	v_exp_f32_e32 v0, v0
	v_mov_b32_e32 v118, v50
	v_pk_mul_f32 v[38:39], v[38:39], v[0:1] op_sel_hi:[1,0]
	v_pk_mul_f32 v[40:41], v[40:41], v[0:1] op_sel_hi:[1,0]
	v_pk_mul_f32 v[32:33], v[32:33], v[0:1] op_sel_hi:[1,0]
	v_pk_mul_f32 v[30:31], v[30:31], v[0:1] op_sel_hi:[1,0]
	v_pk_mul_f32 v[24:25], v[24:25], v[0:1] op_sel_hi:[1,0]
	v_pk_mul_f32 v[22:23], v[22:23], v[0:1] op_sel_hi:[1,0]
	v_pk_mul_f32 v[12:13], v[12:13], v[0:1] op_sel_hi:[1,0]
	v_pk_mul_f32 v[10:11], v[10:11], v[0:1] op_sel_hi:[1,0]
	v_pk_mul_f32 v[8:9], v[8:9], v[0:1] op_sel_hi:[1,0]
	v_pk_mul_f32 v[6:7], v[6:7], v[0:1] op_sel_hi:[1,0]
.LBB0_1284:
	v_max_f32_e32 v0, v59, v59
	v_max_f32_e32 v50, v58, v58
	v_max_f32_e32 v0, v50, v0
	v_max_f32_e32 v50, v61, v61
	v_max_f32_e32 v51, v60, v60
	v_max_f32_e32 v50, v51, v50
	v_max_f32_e32 v51, v73, v73
	v_max_f32_e32 v52, v72, v72
	v_max_f32_e32 v51, v52, v51
	v_max3_f32 v51, v70, v71, v51
	v_max3_f32 v0, v0, v50, v51
	v_max_f32_e32 v50, v69, v69
	v_max_f32_e32 v51, v68, v68
	v_max_f32_e32 v50, v51, v50
	v_max_f32_e32 v51, v45, v45
	v_max_f32_e32 v52, v44, v44
	v_max_f32_e32 v51, v52, v51
	v_max3_f32 v50, v66, v67, v50
	v_max3_f32 v51, v42, v43, v51
	v_max3_f32 v0, v0, v50, v51
	v_mov_b32_e32 v50, v0
	s_nop 1
	v_permlane16_swap_b32_e32 v50, v0
	v_max_f32_e32 v0, v0, v50
	v_mov_b32_e32 v50, v0
	s_nop 1
	v_permlane32_swap_b32_e32 v50, v0
	v_max_f32_e32 v0, v0, v50
	v_add_f32_e32 v50, 0x41000000, v119
	v_cmp_gt_f32_e32 vcc, v0, v50
	s_cbranch_vccz .LBB0_1286
	v_max_f32_e32 v0, v0, v0
	v_max_f32_e32 v50, v119, v119
	v_max_f32_e32 v50, v50, v0
	v_sub_f32_e32 v0, v119, v50
	v_exp_f32_e32 v0, v0
	v_mov_b32_e32 v119, v50
	v_pk_mul_f32 v[34:35], v[34:35], v[0:1] op_sel_hi:[1,0]
	v_pk_mul_f32 v[36:37], v[36:37], v[0:1] op_sel_hi:[1,0]
	v_pk_mul_f32 v[28:29], v[28:29], v[0:1] op_sel_hi:[1,0]
	v_pk_mul_f32 v[26:27], v[26:27], v[0:1] op_sel_hi:[1,0]
	v_pk_mul_f32 v[20:21], v[20:21], v[0:1] op_sel_hi:[1,0]
	v_pk_mul_f32 v[18:19], v[18:19], v[0:1] op_sel_hi:[1,0]
	v_pk_mul_f32 v[16:17], v[16:17], v[0:1] op_sel_hi:[1,0]
	v_pk_mul_f32 v[14:15], v[14:15], v[0:1] op_sel_hi:[1,0]
	v_pk_mul_f32 v[4:5], v[4:5], v[0:1] op_sel_hi:[1,0]
	v_pk_mul_f32 v[2:3], v[2:3], v[0:1] op_sel_hi:[1,0]
